# prompt-group key-split shape (NS,SP) (16,4)->(8,8): 64 half-length sub-items per XCD for a tighter phase-4 tail; phase-5 combine of 8 partials hand-written
# baseline (speedup 1.0000x reference)
; __device__ __forceinline__ int TID() { int t = threadIdx.x; asm volatile("" : "+v"(t)); return t; }
; DI void attn_item(const Params& p, int g, int seq, int hd, int qt, int m, char* smem, int split_j, int sub) {
;     ...
;   const int npairs = (split_j < 0) ? (S >> 6) : (S >> 6) / SPLIT_SP;
;   const int tbase = (split_j < 0) ? 0 : split_j * npairs * 2;
; DI void phase_mixers(const Params& p, int gc, char* smem, int* s_item, int bid) {
;   const int g = gc & 3;
;   const GroupInfo gi = group_info(p, g);
;   const int x = bid & 7;
;   int* ctr = (int*)(p.ws + OFF_MISC) + gc * 8 + x;
;   const int nsplit = (gi.nseq == 1) ? SPLIT_NS : 0;
;   const int nreg = 256 - nsplit;
;   const int nscan_x = gi.nseq * 4, total = nscan_x + nreg + nsplit * SPLIT_SP, nq = gi.S >> 7;
;   for (;;) {
;     __syncthreads();
;     if (TID() == 0) *s_item = atomicAdd(ctr, 1);
;     __syncthreads();
;     const int item = *s_item;
;     if (item >= total) break;
;     if (item < nscan_x) gla_scan_unit(p, g, x * nscan_x + item, smem);
;     else if (item < nscan_x + nreg) { const int ai = item - nscan_x, idx = ai >> 1; attn_item(p, g, idx / nq, x, idx % nq, ai & 1, smem, -1, 0); }
;     else { const int sidx = item - nscan_x - nreg, ai = nreg + sidx / SPLIT_SP, idx = ai >> 1; attn_item(p, g, idx / nq, x, idx % nq, ai & 1, smem, sidx % SPLIT_SP, x * 64 + sidx); }
.LBB0_160:
	v_sub_co_u32_e64 v0, s[22:23], s16, 1
	s_and_b64 s[0:1], s[22:23], exec
	s_cselect_b32 s86, 1, 2
	s_lshl_b32 s50, s16, 3
	v_readlane_b32 s8, v235, 1
	s_add_i32 s24, s50, -7
	s_lshl_b32 s0, s16, 26
	v_readlane_b32 s14, v235, 7
	v_readlane_b32 s15, v235, 8
	s_add_u32 s0, s14, s0
	v_writelane_b32 v231, s0, 23
	s_addc_u32 s0, s15, 0
	v_writelane_b32 v231, s0, 24
	v_readfirstlane_b32 s0, v0
	s_lshl_b32 s1, s0, 3
	s_or_b32 s1, s1, 1
	v_writelane_b32 v231, s1, 25
	s_ashr_i32 s1, s0, 31
	s_lshl_b64 s[0:1], s[0:1], 26
	s_add_u32 s6, s42, s0
	s_addc_u32 s7, s43, s1
	v_readlane_b32 s9, v235, 2
	v_readlane_b32 s10, v235, 3
	v_readlane_b32 s11, v235, 4
	s_and_b64 s[0:1], s[22:23], exec
	v_readlane_b32 s12, v235, 5
	s_cselect_b32 s8, s41, s7
	s_cselect_b32 s9, s40, s6
	s_cselect_b32 s6, 8, 0
	s_cselect_b32 s10, 4, 32
	s_cselect_b32 s11, 0x80, 16
	s_lshl_b64 s[0:1], s[50:51], 2
	v_readlane_b32 s7, v233, 7
	v_readlane_b32 s13, v235, 6
	s_add_u32 s12, s7, s0
	v_readlane_b32 s0, v233, 10
	s_addc_u32 s13, s0, s1
	v_writelane_b32 v231, s12, 26
	s_sub_i32 s0, 0x100, s6
	s_add_i32 s1, s0, s10
	v_writelane_b32 v231, s13, 27
	v_writelane_b32 v231, s10, 28
	v_writelane_b32 v231, s0, 29
	s_lshl_b32 s0, s6, 3
	v_writelane_b32 v231, s1, 30
	s_add_i32 s0, s1, s0
	v_writelane_b32 v231, s0, 31
	s_and_b64 s[0:1], s[22:23], exec
	s_cselect_b32 s0, 7, 4
	v_writelane_b32 v231, s0, 32
	s_add_i32 s0, s11, -1
	v_writelane_b32 v231, s0, 33
	s_and_b64 s[0:1], s[22:23], exec
	s_cselect_b32 s0, 2, 5
	s_cselect_b32 s77, 32, 8
	s_cselect_b32 s6, 14, 11
	s_cselect_b32 s73, 0x100, 32
	s_lshl_b32 s0, s33, s0
	v_writelane_b32 v231, s0, 34
	s_and_b64 s[0:1], s[22:23], exec
	v_cvt_f32_ubyte0_e32 v0, s11
	s_cselect_b32 s0, 8, 5
	v_rcp_iflag_f32_e32 v0, v0
	v_writelane_b32 v231, s0, 35
	s_add_i32 s0, s73, -1
	v_writelane_b32 v231, s0, 36
	s_add_i32 s0, s6, -9
	v_writelane_b32 v231, s6, 37
	s_cmp_lg_u32 s16, 2
	v_writelane_b32 v231, s0, 38
	s_cselect_b64 s[0:1], -1, 0
	v_mul_f32_e32 v0, 0x4f7ffffe, v0
	v_writelane_b32 v231, s0, 39
	s_or_b32 s6, s50, 1
	v_cvt_u32_f32_e32 v0, v0
	v_writelane_b32 v231, s1, 40
	s_cmp_eq_u32 s16, 2
	v_writelane_b32 v231, s16, 41
	s_cselect_b64 s[0:1], -1, 0
	v_writelane_b32 v231, s0, 42
	s_nop 1
	v_writelane_b32 v231, s1, 43
	s_sub_i32 s0, 0, s11
	v_readfirstlane_b32 s1, v0
	s_mul_i32 s0, s0, s1
	s_mul_hi_u32 s0, s1, s0
	s_add_i32 s0, s1, s0
	v_writelane_b32 v231, s0, 44
	v_writelane_b32 v231, s11, 45
	s_lshl_b32 s0, s11, 7
	v_writelane_b32 v231, s0, 46
	v_writelane_b32 v231, s9, 47
	s_add_u32 s0, s9, 0x800
	v_writelane_b32 v231, s8, 48
	s_addc_u32 s1, s8, 0
	v_writelane_b32 v231, s0, 49
	s_nop 1
	v_writelane_b32 v231, s1, 50
	s_xor_b64 s[0:1], s[22:23], -1
	v_writelane_b32 v231, s0, 51
	s_nop 1
	v_writelane_b32 v231, s1, 52
	v_writelane_b32 v231, s22, 53
	s_nop 1
	v_writelane_b32 v231, s23, 54
	v_writelane_b32 v231, s24, 55
	v_writelane_b32 v231, s6, 56
	s_branch .LBB0_164

; __device__ __forceinline__ int TID() { int t = threadIdx.x; asm volatile("" : "+v"(t)); return t; }
; DI void phase_gla_norm(const Params& p, int g, int bid, int nb) {
;   const GroupInfo gi = group_info(p, g);
;   const bf16_t* of = (const bf16_t*)gi.out; const bf16_t* ob = of + (size_t)TOKG * 1024;
;   const bf16_t* proj = (const bf16_t*)(p.ws + OFF_PROJ); bf16_t* dst = (bf16_t*)(p.ws + OFF_H);
;   bf16_t* oa = (bf16_t*)(p.ws + OFF_OA); const bf16_t* oa2 = (const bf16_t*)(p.ws + OFF_OA2);
;   const float lam = *(const float*)(p.ws + OFF_MISC + 1024);
;   const int lane = TID() & 63, wave = TID() >> 6;
;   float gn[16], sg[16];
; #pragma unroll
;   for (int e = 0; e < 16; ++e) { gn[e] = p.gla_norm_g[(lane & 15) * 16 + e]; sg[e] = p.subln_g[(lane & 7) * 16 + e] * 0.8f; }
;   for (int tok = bid * 4 + wave; tok < TOKG; tok += nb * 4) {
;     const size_t base = (size_t)tok * 1024 + lane * 16;
;     const u32x4 f0 = *(const u32x4*)(of + base), f1 = *(const u32x4*)(of + base + 8), b0 = *(const u32x4*)(ob + base), b1 = *(const u32x4*)(ob + base + 8);
;     const u32x4 g0 = *(const u32x4*)(proj + (size_t)tok * NPROJ + POG + lane * 16), g1 = *(const u32x4*)(proj + (size_t)tok * NPROJ + POG + lane * 16 + 8);
;     const u32x4 a0 = *(const u32x4*)(oa + base), a1 = *(const u32x4*)(oa + base + 8), c0 = *(const u32x4*)(oa2 + base), c1 = *(const u32x4*)(oa2 + base + 8);
;     ...
;     if (gi.nseq == 1 && tok >= (128 - SPLIT_NS / 2) * 128) {
;       const int x = lane >> 3, row = tok & 127, ai0 = (tok >> 7) * 2 - (256 - SPLIT_NS);
;       const bf16_t* po = (const bf16_t*)(p.ws + OFF_PO); const float* pl = (const float*)(p.ws + OFF_PL);
.LBB0_228:
	s_andn2_b64 vcc, exec, s[0:1]
	s_cbranch_vccnz .LBB0_733
	s_cmp_lt_i32 s86, 4
	s_mov_b64 s[0:1], -1
	s_cbranch_scc1 .LBB0_241
	s_cmp_gt_i32 s86, 4
	s_cbranch_scc0 .LBB0_239
	v_readlane_b32 s0, v233, 3
	v_readlane_b32 s1, v233, 4
	v_mov_b32_e32 v17, v195
	v_mov_b32_e32 v0, v195
	s_nop 2
	global_load_dword v104, v193, s[0:1]
	v_readlane_b32 s0, v233, 60
	v_ashrrev_i32_e32 v16, 6, v0
	v_readlane_b32 s1, v233, 61
	v_add_u32_e32 v148, s0, v16
	s_movk_i32 s0, 0x4000
	v_cmp_gt_i32_e32 vcc, s0, v148
	s_and_saveexec_b64 s[6:7], vcc
	s_cbranch_execz .LBB0_238
	v_lshlrev_b32_e32 v0, 4, v17
	v_and_b32_e32 v34, 0x70, v0
	v_lshlrev_b32_e32 v0, 6, v17
	v_readlane_b32 s8, v235, 29
	v_and_b32_e32 v12, 0x3c0, v0
	v_readlane_b32 s9, v235, 30
	v_readlane_b32 s10, v235, 31
	v_readlane_b32 s11, v235, 32
	v_readlane_b32 s12, v235, 33
	v_readlane_b32 s13, v235, 34
	v_readlane_b32 s14, v235, 35
	v_readlane_b32 s15, v235, 36
	v_readlane_b32 s16, v235, 37
	v_readlane_b32 s17, v235, 38
	v_readlane_b32 s18, v235, 39
	v_readlane_b32 s19, v235, 40
	v_readlane_b32 s20, v235, 41
	v_readlane_b32 s21, v235, 42
	v_readlane_b32 s22, v235, 43
	v_readlane_b32 s23, v235, 44
	s_waitcnt lgkmcnt(1)
	global_load_dwordx4 v[0:3], v12, s[16:17] offset:48
	s_waitcnt lgkmcnt(0)
	global_load_dwordx4 v[4:7], v12, s[16:17] offset:32
	global_load_dwordx4 v[8:11], v12, s[16:17] offset:16
	s_nop 0
	global_load_dwordx4 v[12:15], v12, s[16:17]
	v_readlane_b32 s8, v235, 13
	v_lshlrev_b32_e32 v30, 2, v34
	v_readlane_b32 s22, v235, 27
	v_readlane_b32 s23, v235, 28
	s_nop 4
	global_load_dwordx4 v[18:21], v30, s[22:23] offset:48
	global_load_dwordx4 v[22:25], v30, s[22:23] offset:32
	global_load_dwordx4 v[26:29], v30, s[22:23] offset:16
	s_nop 0
	global_load_dwordx4 v[30:33], v30, s[22:23]
	s_mov_b32 s0, 0x3f4ccccd
	v_lshlrev_b32_e32 v192, 1, v34
	v_readlane_b32 s9, v235, 14
	v_readlane_b32 s22, v231, 53
	v_readlane_b32 s23, v231, 54
	s_waitcnt vmcnt(8)
	v_xor_b32_e32 v149, 0x80000000, v104
	v_mov_b32_e32 v105, v104
	v_mov_b32_e32 v125, v193
	s_mov_b64 s[8:9], 0
	v_readlane_b32 s10, v235, 15
	v_readlane_b32 s11, v235, 16
	v_readlane_b32 s12, v235, 17
	v_readlane_b32 s13, v235, 18
	v_readlane_b32 s14, v235, 19
	v_readlane_b32 s15, v235, 20
	v_readlane_b32 s16, v235, 21
	v_readlane_b32 s17, v235, 22
	v_readlane_b32 s18, v235, 23
	v_readlane_b32 s19, v235, 24
	v_readlane_b32 s20, v235, 25
	v_readlane_b32 s21, v235, 26
	s_waitcnt vmcnt(3)
	v_pk_mul_f32 v[120:121], v[20:21], s[0:1] op_sel_hi:[1,0]
	v_and_b32_e32 v20, 64, v213
	v_pk_mul_f32 v[118:119], v[18:19], s[0:1] op_sel_hi:[1,0]
	v_xor_b32_e32 v19, 1, v213
	v_add_u32_e32 v20, 64, v20
	v_cmp_lt_i32_e32 vcc, v19, v20
	s_waitcnt vmcnt(0)
	v_pk_mul_f32 v[106:107], v[30:31], s[0:1] op_sel_hi:[1,0]
	v_pk_mul_f32 v[108:109], v[32:33], s[0:1] op_sel_hi:[1,0]
	v_cndmask_b32_e32 v19, v213, v19, vcc
	v_lshlrev_b32_e32 v150, 2, v19
	v_xor_b32_e32 v19, 2, v213
	v_cmp_lt_i32_e32 vcc, v19, v20
	v_pk_mul_f32 v[110:111], v[26:27], s[0:1] op_sel_hi:[1,0]
	v_pk_mul_f32 v[112:113], v[28:29], s[0:1] op_sel_hi:[1,0]
	v_cndmask_b32_e32 v19, v213, v19, vcc
	v_lshlrev_b32_e32 v151, 2, v19
	v_xor_b32_e32 v19, 4, v213
	v_cmp_lt_i32_e32 vcc, v19, v20
	v_pk_mul_f32 v[114:115], v[22:23], s[0:1] op_sel_hi:[1,0]
	v_pk_mul_f32 v[116:117], v[24:25], s[0:1] op_sel_hi:[1,0]
	v_cndmask_b32_e32 v19, v213, v19, vcc
	v_readlane_b32 s0, v233, 5
	v_and_b32_e32 v18, 63, v17
	v_lshlrev_b32_e32 v17, 3, v17
	v_lshlrev_b32_e32 v152, 2, v19
	v_xor_b32_e32 v19, 8, v213
	v_readlane_b32 s1, v233, 6
	v_and_b32_e32 v17, 0x1c0, v17
	v_cmp_lt_i32_e32 vcc, v19, v20
	v_lshl_add_u64 v[122:123], s[0:1], 0, v[192:193]
	v_readlane_b32 s0, v233, 60
	v_cndmask_b32_e32 v19, v213, v19, vcc
	v_add_u32_e32 v154, 0xfffff840, v17
	v_add_u32_e32 v155, 0xfffffc44, v17
	v_ashrrev_i32_e32 v17, 31, v16
	v_readlane_b32 s1, v233, 61
	v_lshlrev_b32_e32 v153, 2, v19
	v_lshlrev_b32_e32 v124, 5, v18
	v_lshl_add_u64 v[16:17], s[0:1], 0, v[16:17]
	v_mov_b64_e32 v[18:19], s[96:97]
	v_mad_u64_u32 v[126:127], s[0:1], v16, s2, v[18:19]
	v_readlane_b32 s0, v231, 10
	v_mad_i32_i24 v127, v17, s2, v127
	v_lshlrev_b64 v[16:17], 11, v[16:17]
	v_readlane_b32 s1, v231, 11
	v_lshl_add_u64 v[130:131], s[96:97], 0, v[16:17]
	s_nop 0
	v_lshl_add_u64 v[128:129], s[0:1], 0, v[16:17]
	v_readlane_b32 s0, v231, 2
	v_readlane_b32 s1, v231, 3
	s_nop 1
	v_lshl_add_u64 v[132:133], s[0:1], 0, v[16:17]
	s_branch .LBB0_234

; DI void phase_gla_norm(const Params& p, int g, int bid, int nb) {
;     ...
;   for (int tok = bid * 4 + wave; tok < TOKG; tok += nb * 4) {
;     const size_t base = (size_t)tok * 1024 + lane * 16;
;     const u32x4 f0 = *(const u32x4*)(of + base), f1 = *(const u32x4*)(of + base + 8), b0 = *(const u32x4*)(ob + base), b1 = *(const u32x4*)(ob + base + 8);
;     const u32x4 g0 = *(const u32x4*)(proj + (size_t)tok * NPROJ + POG + lane * 16), g1 = *(const u32x4*)(proj + (size_t)tok * NPROJ + POG + lane * 16 + 8);
;     const u32x4 a0 = *(const u32x4*)(oa + base), a1 = *(const u32x4*)(oa + base + 8), c0 = *(const u32x4*)(oa2 + base), c1 = *(const u32x4*)(oa2 + base + 8);
;     ...
;     if (gi.nseq == 1 && tok >= (128 - SPLIT_NS / 2) * 128) {
;       const int x = lane >> 3, row = tok & 127, ai0 = (tok >> 7) * 2 - (256 - SPLIT_NS);
;       const bf16_t* po = (const bf16_t*)(p.ws + OFF_PO); const float* pl = (const float*)(p.ws + OFF_PL);
; #pragma unroll
;       for (int m = 0; m < 2; ++m) {
;         float acc[16], lsum = 0.f;
; #pragma unroll
;         for (int e = 0; e < 16; ++e) acc[e] = 0.f;
; #pragma unroll
;         for (int j = 0; j < SPLIT_SP; ++j) {
;           const int sub = x * 64 + (ai0 + m) * SPLIT_SP + j;
;           lsum += pl[sub * 128 + row];
;           const bf16_t* src = po + (size_t)sub * 16384 + row * 128 + (lane & 7) * 16;
;           unpack8(*(const u32x4*)src, t);
.LBB0_234:
	v_lshl_add_u64 v[16:17], v[128:129], 0, v[124:125]
	global_load_dwordx4 v[28:31], v[16:17], off offset:16
	global_load_dwordx4 v[36:39], v[16:17], off
	v_lshl_add_u64 v[16:17], v[132:133], 0, v[124:125]
	global_load_dwordx4 v[24:27], v[16:17], off
	global_load_dwordx4 v[32:35], v[16:17], off offset:-16
	v_lshl_add_u64 v[16:17], v[126:127], 0, v[124:125]
	s_mov_b64 s[0:1], 0x46c9000
	v_lshl_add_u64 v[18:19], v[16:17], 0, s[0:1]
	v_add_co_u32_e32 v16, vcc, 0x46c9000, v16
	v_lshl_add_u64 v[134:135], v[130:131], 0, v[124:125]
	s_nop 0
	v_addc_co_u32_e32 v17, vcc, 0, v17, vcc
	global_load_dwordx4 v[20:23], v[16:17], off
	s_nop 0
	global_load_dwordx4 v[16:19], v[18:19], off offset:16
	s_mov_b64 s[0:1], 0x1a9c8000
	v_lshl_add_u64 v[136:137], v[134:135], 0, s[0:1]
	s_movk_i32 s0, 0x3e00
	v_cmp_gt_i32_e32 vcc, s0, v148
	v_readlane_b32 s0, v231, 51
	v_readlane_b32 s1, v231, 52
	s_or_b64 s[0:1], s[0:1], vcc
	s_and_saveexec_b64 s[10:11], s[0:1]
	s_xor_b64 s[0:1], exec, s[10:11]
	s_cbranch_execz .LBB0_236
	s_mov_b64 s[10:11], 0x1c9c8000
	v_add_co_u32_e32 v42, vcc, 0x1c9c8000, v134
	v_lshl_add_u64 v[40:41], v[134:135], 0, s[10:11]
	s_nop 0
	v_addc_co_u32_e32 v43, vcc, 0, v135, vcc
	global_load_dwordx4 v[48:51], v[42:43], off
	s_nop 0
	global_load_dwordx4 v[40:43], v[40:41], off offset:16
	s_nop 0
	global_load_dwordx4 v[54:57], v[136:137], off offset:16
	global_load_dwordx4 v[58:61], v[136:137], off
	s_waitcnt vmcnt(3)
	v_lshlrev_b32_e32 v46, 16, v48
	v_and_b32_e32 v47, 0xffff0000, v48
	v_lshlrev_b32_e32 v48, 16, v49
	s_waitcnt vmcnt(0)
	v_lshlrev_b32_e32 v44, 16, v58
	v_and_b32_e32 v45, 0xffff0000, v58
	v_pk_fma_f32 v[44:45], v[104:105], v[46:47], v[44:45] neg_lo:[1,0,0] neg_hi:[1,0,0]
	v_lshlrev_b32_e32 v46, 16, v59
	v_and_b32_e32 v47, 0xffff0000, v59
	v_and_b32_e32 v49, 0xffff0000, v49
	v_pk_fma_f32 v[46:47], v[104:105], v[48:49], v[46:47] neg_lo:[1,0,0] neg_hi:[1,0,0]
	v_lshlrev_b32_e32 v48, 16, v60
	v_and_b32_e32 v49, 0xffff0000, v60
	v_lshlrev_b32_e32 v52, 16, v50
	v_and_b32_e32 v53, 0xffff0000, v50
	v_pk_fma_f32 v[48:49], v[104:105], v[52:53], v[48:49] neg_lo:[1,0,0] neg_hi:[1,0,0]
	v_lshlrev_b32_e32 v52, 16, v61
	v_and_b32_e32 v53, 0xffff0000, v61
	v_lshlrev_b32_e32 v50, 16, v51
	v_and_b32_e32 v51, 0xffff0000, v51
	v_pk_fma_f32 v[50:51], v[104:105], v[50:51], v[52:53] neg_lo:[1,0,0] neg_hi:[1,0,0]
	v_lshlrev_b32_e32 v52, 16, v54
	v_and_b32_e32 v53, 0xffff0000, v54
	v_lshlrev_b32_e32 v58, 16, v40
	v_and_b32_e32 v59, 0xffff0000, v40
	v_lshlrev_b32_e32 v54, 16, v55
	v_and_b32_e32 v55, 0xffff0000, v55
	v_lshlrev_b32_e32 v40, 16, v41
	v_and_b32_e32 v41, 0xffff0000, v41
	v_pk_fma_f32 v[52:53], v[104:105], v[58:59], v[52:53] neg_lo:[1,0,0] neg_hi:[1,0,0]
	v_pk_fma_f32 v[40:41], v[104:105], v[40:41], v[54:55] neg_lo:[1,0,0] neg_hi:[1,0,0]
	v_lshlrev_b32_e32 v54, 16, v56
	v_and_b32_e32 v55, 0xffff0000, v56
	v_lshlrev_b32_e32 v58, 16, v42
	v_and_b32_e32 v59, 0xffff0000, v42
	v_lshlrev_b32_e32 v56, 16, v57
	v_and_b32_e32 v57, 0xffff0000, v57
	v_lshlrev_b32_e32 v42, 16, v43
	v_and_b32_e32 v43, 0xffff0000, v43
	v_pk_fma_f32 v[54:55], v[104:105], v[58:59], v[54:55] neg_lo:[1,0,0] neg_hi:[1,0,0]
	v_pk_fma_f32 v[42:43], v[104:105], v[42:43], v[56:57] neg_lo:[1,0,0] neg_hi:[1,0,0]
.LBB0_236:
	s_andn2_saveexec_b64 s[0:1], s[0:1]
	s_cbranch_execz .LBB0_233
	v_lshrrev_b32_e32 v40, 3, v148
	v_and_b32_e32 v100, 0x7f, v148
	v_and_b32_e32 v58, 0xffffff0, v40
	v_add_u32_e32 v52, v154, v58
	v_lshlrev_b32_e32 v192, 8, v100
	v_lshl_add_u64 v[200:201], v[122:123], 0, v[192:193]
	v_lshl_or_b32 v192, v52, 7, v100
	v_lshl_add_u64 v[202:203], v[192:193], 2, s[56:57]
	v_mov_b32_e32 v53, v193
	v_lshlrev_b64 v[40:41], 15, v[52:53]
	v_lshl_add_u64 v[200:201], v[200:201], 0, v[40:41]
	s_mov_b64 s[10:11], 0x1000
	v_lshl_add_u64 v[204:205], v[202:203], 0, s[10:11]
	s_mov_b64 s[10:11], 0x8000
	global_load_dword v138, v[202:203], off
	global_load_dword v139, v[202:203], off offset:512
	global_load_dword v140, v[202:203], off offset:1024
	global_load_dword v141, v[202:203], off offset:1536
	global_load_dword v142, v[202:203], off offset:2048
	global_load_dword v143, v[202:203], off offset:2560
	global_load_dword v144, v[202:203], off offset:3072
	global_load_dword v145, v[202:203], off offset:3584
	global_load_dword v146, v[204:205], off
	global_load_dword v147, v[204:205], off offset:512
	global_load_dword v156, v[204:205], off offset:1024
	global_load_dword v157, v[204:205], off offset:1536
	global_load_dword v158, v[204:205], off offset:2048
	global_load_dword v159, v[204:205], off offset:2560
	global_load_dword v160, v[204:205], off offset:3072
	global_load_dword v196, v[204:205], off offset:3584
	global_load_dwordx4 v[40:43], v[200:201], off
	global_load_dwordx4 v[44:47], v[200:201], off offset:16
	v_lshl_add_u64 v[200:201], v[200:201], 0, s[10:11]
	global_load_dwordx4 v[48:51], v[200:201], off
	global_load_dwordx4 v[52:55], v[200:201], off offset:16
	v_lshl_add_u64 v[200:201], v[200:201], 0, s[10:11]
	global_load_dwordx4 v[56:59], v[200:201], off
	global_load_dwordx4 v[60:63], v[200:201], off offset:16
	v_lshl_add_u64 v[200:201], v[200:201], 0, s[10:11]
	global_load_dwordx4 v[64:67], v[200:201], off
	global_load_dwordx4 v[68:71], v[200:201], off offset:16
	v_lshl_add_u64 v[200:201], v[200:201], 0, s[10:11]
	global_load_dwordx4 v[72:75], v[200:201], off
	global_load_dwordx4 v[76:79], v[200:201], off offset:16
	v_lshl_add_u64 v[200:201], v[200:201], 0, s[10:11]
	global_load_dwordx4 v[80:83], v[200:201], off
	global_load_dwordx4 v[84:87], v[200:201], off offset:16
	v_lshl_add_u64 v[200:201], v[200:201], 0, s[10:11]
	global_load_dwordx4 v[88:91], v[200:201], off
	global_load_dwordx4 v[92:95], v[200:201], off offset:16
	v_lshl_add_u64 v[200:201], v[200:201], 0, s[10:11]
	global_load_dwordx4 v[96:99], v[200:201], off
	global_load_dwordx4 v[100:103], v[200:201], off offset:16
	v_lshl_add_u64 v[200:201], v[200:201], 0, s[10:11]
	s_waitcnt vmcnt(0)
; DI void phase_gla_norm(const Params& p, int g, int bid, int nb) {
;     ...
;       for (int m = 0; m < 2; ++m) {
;         float acc[16], lsum = 0.f;
; #pragma unroll
;         for (int e = 0; e < 16; ++e) acc[e] = 0.f;
; #pragma unroll
;         for (int j = 0; j < SPLIT_SP; ++j) {
;           const int sub = x * 64 + (ai0 + m) * SPLIT_SP + j;
;           lsum += pl[sub * 128 + row];
;           const bf16_t* src = po + (size_t)sub * 16384 + row * 128 + (lane & 7) * 16;
;           unpack8(*(const u32x4*)src, t);
; #pragma unroll
;           for (int e = 0; e < 8; ++e) acc[e] += t[e];
;           unpack8(*(const u32x4*)(src + 8), t);
; #pragma unroll
;           for (int e = 0; e < 8; ++e) acc[8 + e] += t[e];
;         }
	v_lshlrev_b32_e32 v161, 16, v40
	v_lshlrev_b32_e32 v206, 16, v48
	v_add_f32_e32 v161, v161, v206
	v_lshlrev_b32_e32 v206, 16, v56
	v_add_f32_e32 v161, v161, v206
	v_lshlrev_b32_e32 v206, 16, v64
	v_add_f32_e32 v161, v161, v206
	v_lshlrev_b32_e32 v206, 16, v72
	v_add_f32_e32 v161, v161, v206
	v_lshlrev_b32_e32 v206, 16, v80
	v_add_f32_e32 v161, v161, v206
	v_lshlrev_b32_e32 v206, 16, v88
	v_add_f32_e32 v161, v161, v206
	v_lshlrev_b32_e32 v206, 16, v96
	v_add_f32_e32 v161, v161, v206
	v_and_b32_e32 v162, 0xffff0000, v40
	v_and_b32_e32 v206, 0xffff0000, v48
	v_add_f32_e32 v162, v162, v206
	v_and_b32_e32 v206, 0xffff0000, v56
	v_add_f32_e32 v162, v162, v206
	v_and_b32_e32 v206, 0xffff0000, v64
	v_add_f32_e32 v162, v162, v206
	v_and_b32_e32 v206, 0xffff0000, v72
	v_add_f32_e32 v162, v162, v206
	v_and_b32_e32 v206, 0xffff0000, v80
	v_add_f32_e32 v162, v162, v206
	v_and_b32_e32 v206, 0xffff0000, v88
	v_add_f32_e32 v162, v162, v206
	v_and_b32_e32 v206, 0xffff0000, v96
	v_add_f32_e32 v162, v162, v206
	v_lshlrev_b32_e32 v163, 16, v41
	v_lshlrev_b32_e32 v206, 16, v49
	v_add_f32_e32 v163, v163, v206
	v_lshlrev_b32_e32 v206, 16, v57
	v_add_f32_e32 v163, v163, v206
	v_lshlrev_b32_e32 v206, 16, v65
	v_add_f32_e32 v163, v163, v206
	v_lshlrev_b32_e32 v206, 16, v73
	v_add_f32_e32 v163, v163, v206
	v_lshlrev_b32_e32 v206, 16, v81
	v_add_f32_e32 v163, v163, v206
	v_lshlrev_b32_e32 v206, 16, v89
	v_add_f32_e32 v163, v163, v206
	v_lshlrev_b32_e32 v206, 16, v97
	v_add_f32_e32 v163, v163, v206
	v_and_b32_e32 v164, 0xffff0000, v41
	v_and_b32_e32 v206, 0xffff0000, v49
	v_add_f32_e32 v164, v164, v206
	v_and_b32_e32 v206, 0xffff0000, v57
	v_add_f32_e32 v164, v164, v206
	v_and_b32_e32 v206, 0xffff0000, v65
	v_add_f32_e32 v164, v164, v206
	v_and_b32_e32 v206, 0xffff0000, v73
	v_add_f32_e32 v164, v164, v206
	v_and_b32_e32 v206, 0xffff0000, v81
	v_add_f32_e32 v164, v164, v206
	v_and_b32_e32 v206, 0xffff0000, v89
	v_add_f32_e32 v164, v164, v206
	v_and_b32_e32 v206, 0xffff0000, v97
	v_add_f32_e32 v164, v164, v206
	v_lshlrev_b32_e32 v165, 16, v42
	v_lshlrev_b32_e32 v206, 16, v50
	v_add_f32_e32 v165, v165, v206
	v_lshlrev_b32_e32 v206, 16, v58
	v_add_f32_e32 v165, v165, v206
	v_lshlrev_b32_e32 v206, 16, v66
	v_add_f32_e32 v165, v165, v206
	v_lshlrev_b32_e32 v206, 16, v74
	v_add_f32_e32 v165, v165, v206
	v_lshlrev_b32_e32 v206, 16, v82
	v_add_f32_e32 v165, v165, v206
	v_lshlrev_b32_e32 v206, 16, v90
	v_add_f32_e32 v165, v165, v206
	v_lshlrev_b32_e32 v206, 16, v98
	v_add_f32_e32 v165, v165, v206
	v_and_b32_e32 v166, 0xffff0000, v42
	v_and_b32_e32 v206, 0xffff0000, v50
	v_add_f32_e32 v166, v166, v206
	v_and_b32_e32 v206, 0xffff0000, v58
	v_add_f32_e32 v166, v166, v206
	v_and_b32_e32 v206, 0xffff0000, v66
	v_add_f32_e32 v166, v166, v206
	v_and_b32_e32 v206, 0xffff0000, v74
	v_add_f32_e32 v166, v166, v206
	v_and_b32_e32 v206, 0xffff0000, v82
	v_add_f32_e32 v166, v166, v206
	v_and_b32_e32 v206, 0xffff0000, v90
	v_add_f32_e32 v166, v166, v206
	v_and_b32_e32 v206, 0xffff0000, v98
	v_add_f32_e32 v166, v166, v206
	v_lshlrev_b32_e32 v167, 16, v43
	v_lshlrev_b32_e32 v206, 16, v51
	v_add_f32_e32 v167, v167, v206
	v_lshlrev_b32_e32 v206, 16, v59
	v_add_f32_e32 v167, v167, v206
	v_lshlrev_b32_e32 v206, 16, v67
	v_add_f32_e32 v167, v167, v206
	v_lshlrev_b32_e32 v206, 16, v75
	v_add_f32_e32 v167, v167, v206
	v_lshlrev_b32_e32 v206, 16, v83
	v_add_f32_e32 v167, v167, v206
	v_lshlrev_b32_e32 v206, 16, v91
	v_add_f32_e32 v167, v167, v206
	v_lshlrev_b32_e32 v206, 16, v99
	v_add_f32_e32 v167, v167, v206
	v_and_b32_e32 v168, 0xffff0000, v43
	v_and_b32_e32 v206, 0xffff0000, v51
	v_add_f32_e32 v168, v168, v206
	v_and_b32_e32 v206, 0xffff0000, v59
	v_add_f32_e32 v168, v168, v206
	v_and_b32_e32 v206, 0xffff0000, v67
	v_add_f32_e32 v168, v168, v206
	v_and_b32_e32 v206, 0xffff0000, v75
	v_add_f32_e32 v168, v168, v206
	v_and_b32_e32 v206, 0xffff0000, v83
	v_add_f32_e32 v168, v168, v206
	v_and_b32_e32 v206, 0xffff0000, v91
	v_add_f32_e32 v168, v168, v206
	v_and_b32_e32 v206, 0xffff0000, v99
	v_add_f32_e32 v168, v168, v206
	v_lshlrev_b32_e32 v169, 16, v44
	v_lshlrev_b32_e32 v206, 16, v52
	v_add_f32_e32 v169, v169, v206
	v_lshlrev_b32_e32 v206, 16, v60
	v_add_f32_e32 v169, v169, v206
	v_lshlrev_b32_e32 v206, 16, v68
	v_add_f32_e32 v169, v169, v206
	v_lshlrev_b32_e32 v206, 16, v76
	v_add_f32_e32 v169, v169, v206
	v_lshlrev_b32_e32 v206, 16, v84
	v_add_f32_e32 v169, v169, v206
	v_lshlrev_b32_e32 v206, 16, v92
	v_add_f32_e32 v169, v169, v206
	v_lshlrev_b32_e32 v206, 16, v100
	v_add_f32_e32 v169, v169, v206
	v_and_b32_e32 v170, 0xffff0000, v44
	v_and_b32_e32 v206, 0xffff0000, v52
	v_add_f32_e32 v170, v170, v206
	v_and_b32_e32 v206, 0xffff0000, v60
	v_add_f32_e32 v170, v170, v206
	v_and_b32_e32 v206, 0xffff0000, v68
	v_add_f32_e32 v170, v170, v206
	v_and_b32_e32 v206, 0xffff0000, v76
	v_add_f32_e32 v170, v170, v206
	v_and_b32_e32 v206, 0xffff0000, v84
	v_add_f32_e32 v170, v170, v206
	v_and_b32_e32 v206, 0xffff0000, v92
	v_add_f32_e32 v170, v170, v206
	v_and_b32_e32 v206, 0xffff0000, v100
	v_add_f32_e32 v170, v170, v206
	v_lshlrev_b32_e32 v171, 16, v45
	v_lshlrev_b32_e32 v206, 16, v53
	v_add_f32_e32 v171, v171, v206
	v_lshlrev_b32_e32 v206, 16, v61
	v_add_f32_e32 v171, v171, v206
	v_lshlrev_b32_e32 v206, 16, v69
	v_add_f32_e32 v171, v171, v206
	v_lshlrev_b32_e32 v206, 16, v77
	v_add_f32_e32 v171, v171, v206
	v_lshlrev_b32_e32 v206, 16, v85
	v_add_f32_e32 v171, v171, v206
	v_lshlrev_b32_e32 v206, 16, v93
	v_add_f32_e32 v171, v171, v206
	v_lshlrev_b32_e32 v206, 16, v101
	v_add_f32_e32 v171, v171, v206
	v_and_b32_e32 v172, 0xffff0000, v45
	v_and_b32_e32 v206, 0xffff0000, v53
	v_add_f32_e32 v172, v172, v206
; DI void phase_gla_norm(const Params& p, int g, int bid, int nb) {
;     ...
;       for (int m = 0; m < 2; ++m) {
;         float acc[16], lsum = 0.f;
; #pragma unroll
;         for (int e = 0; e < 16; ++e) acc[e] = 0.f;
; #pragma unroll
;         for (int j = 0; j < SPLIT_SP; ++j) {
;           const int sub = x * 64 + (ai0 + m) * SPLIT_SP + j;
;           lsum += pl[sub * 128 + row];
;           const bf16_t* src = po + (size_t)sub * 16384 + row * 128 + (lane & 7) * 16;
;           unpack8(*(const u32x4*)src, t);
; #pragma unroll
;           for (int e = 0; e < 8; ++e) acc[e] += t[e];
;           unpack8(*(const u32x4*)(src + 8), t);
; #pragma unroll
;           for (int e = 0; e < 8; ++e) acc[8 + e] += t[e];
;         }
	v_and_b32_e32 v206, 0xffff0000, v61
	v_add_f32_e32 v172, v172, v206
	v_and_b32_e32 v206, 0xffff0000, v69
	v_add_f32_e32 v172, v172, v206
	v_and_b32_e32 v206, 0xffff0000, v77
	v_add_f32_e32 v172, v172, v206
	v_and_b32_e32 v206, 0xffff0000, v85
	v_add_f32_e32 v172, v172, v206
	v_and_b32_e32 v206, 0xffff0000, v93
	v_add_f32_e32 v172, v172, v206
	v_and_b32_e32 v206, 0xffff0000, v101
	v_add_f32_e32 v172, v172, v206
	v_lshlrev_b32_e32 v173, 16, v46
	v_lshlrev_b32_e32 v206, 16, v54
	v_add_f32_e32 v173, v173, v206
	v_lshlrev_b32_e32 v206, 16, v62
	v_add_f32_e32 v173, v173, v206
	v_lshlrev_b32_e32 v206, 16, v70
	v_add_f32_e32 v173, v173, v206
	v_lshlrev_b32_e32 v206, 16, v78
	v_add_f32_e32 v173, v173, v206
	v_lshlrev_b32_e32 v206, 16, v86
	v_add_f32_e32 v173, v173, v206
	v_lshlrev_b32_e32 v206, 16, v94
	v_add_f32_e32 v173, v173, v206
	v_lshlrev_b32_e32 v206, 16, v102
	v_add_f32_e32 v173, v173, v206
	v_and_b32_e32 v174, 0xffff0000, v46
	v_and_b32_e32 v206, 0xffff0000, v54
	v_add_f32_e32 v174, v174, v206
	v_and_b32_e32 v206, 0xffff0000, v62
	v_add_f32_e32 v174, v174, v206
	v_and_b32_e32 v206, 0xffff0000, v70
	v_add_f32_e32 v174, v174, v206
	v_and_b32_e32 v206, 0xffff0000, v78
	v_add_f32_e32 v174, v174, v206
	v_and_b32_e32 v206, 0xffff0000, v86
	v_add_f32_e32 v174, v174, v206
	v_and_b32_e32 v206, 0xffff0000, v94
	v_add_f32_e32 v174, v174, v206
	v_and_b32_e32 v206, 0xffff0000, v102
	v_add_f32_e32 v174, v174, v206
	v_lshlrev_b32_e32 v175, 16, v47
	v_lshlrev_b32_e32 v206, 16, v55
	v_add_f32_e32 v175, v175, v206
	v_lshlrev_b32_e32 v206, 16, v63
	v_add_f32_e32 v175, v175, v206
	v_lshlrev_b32_e32 v206, 16, v71
	v_add_f32_e32 v175, v175, v206
	v_lshlrev_b32_e32 v206, 16, v79
	v_add_f32_e32 v175, v175, v206
	v_lshlrev_b32_e32 v206, 16, v87
	v_add_f32_e32 v175, v175, v206
	v_lshlrev_b32_e32 v206, 16, v95
	v_add_f32_e32 v175, v175, v206
	v_lshlrev_b32_e32 v206, 16, v103
	v_add_f32_e32 v175, v175, v206
	v_and_b32_e32 v176, 0xffff0000, v47
	v_and_b32_e32 v206, 0xffff0000, v55
	v_add_f32_e32 v176, v176, v206
	v_and_b32_e32 v206, 0xffff0000, v63
	v_add_f32_e32 v176, v176, v206
	v_and_b32_e32 v206, 0xffff0000, v71
	v_add_f32_e32 v176, v176, v206
	v_and_b32_e32 v206, 0xffff0000, v79
	v_add_f32_e32 v176, v176, v206
	v_and_b32_e32 v206, 0xffff0000, v87
	v_add_f32_e32 v176, v176, v206
	v_and_b32_e32 v206, 0xffff0000, v95
	v_add_f32_e32 v176, v176, v206
	v_and_b32_e32 v206, 0xffff0000, v103
	v_add_f32_e32 v176, v176, v206
	global_load_dwordx4 v[40:43], v[200:201], off
	global_load_dwordx4 v[44:47], v[200:201], off offset:16
	v_lshl_add_u64 v[200:201], v[200:201], 0, s[10:11]
	global_load_dwordx4 v[48:51], v[200:201], off
	global_load_dwordx4 v[52:55], v[200:201], off offset:16
	v_lshl_add_u64 v[200:201], v[200:201], 0, s[10:11]
	global_load_dwordx4 v[56:59], v[200:201], off
	global_load_dwordx4 v[60:63], v[200:201], off offset:16
	v_lshl_add_u64 v[200:201], v[200:201], 0, s[10:11]
	global_load_dwordx4 v[64:67], v[200:201], off
	global_load_dwordx4 v[68:71], v[200:201], off offset:16
	v_lshl_add_u64 v[200:201], v[200:201], 0, s[10:11]
	global_load_dwordx4 v[72:75], v[200:201], off
	global_load_dwordx4 v[76:79], v[200:201], off offset:16
	v_lshl_add_u64 v[200:201], v[200:201], 0, s[10:11]
	global_load_dwordx4 v[80:83], v[200:201], off
	global_load_dwordx4 v[84:87], v[200:201], off offset:16
	v_lshl_add_u64 v[200:201], v[200:201], 0, s[10:11]
	global_load_dwordx4 v[88:91], v[200:201], off
	global_load_dwordx4 v[92:95], v[200:201], off offset:16
	v_lshl_add_u64 v[200:201], v[200:201], 0, s[10:11]
	global_load_dwordx4 v[96:99], v[200:201], off
	global_load_dwordx4 v[100:103], v[200:201], off offset:16
	v_lshl_add_u64 v[200:201], v[200:201], 0, s[10:11]
	s_waitcnt vmcnt(0)
	v_lshlrev_b32_e32 v177, 16, v40
	v_lshlrev_b32_e32 v206, 16, v48
	v_add_f32_e32 v177, v177, v206
	v_lshlrev_b32_e32 v206, 16, v56
	v_add_f32_e32 v177, v177, v206
	v_lshlrev_b32_e32 v206, 16, v64
	v_add_f32_e32 v177, v177, v206
	v_lshlrev_b32_e32 v206, 16, v72
	v_add_f32_e32 v177, v177, v206
	v_lshlrev_b32_e32 v206, 16, v80
	v_add_f32_e32 v177, v177, v206
	v_lshlrev_b32_e32 v206, 16, v88
	v_add_f32_e32 v177, v177, v206
	v_lshlrev_b32_e32 v206, 16, v96
	v_add_f32_e32 v177, v177, v206
	v_and_b32_e32 v178, 0xffff0000, v40
	v_and_b32_e32 v206, 0xffff0000, v48
	v_add_f32_e32 v178, v178, v206
	v_and_b32_e32 v206, 0xffff0000, v56
	v_add_f32_e32 v178, v178, v206
	v_and_b32_e32 v206, 0xffff0000, v64
	v_add_f32_e32 v178, v178, v206
	v_and_b32_e32 v206, 0xffff0000, v72
	v_add_f32_e32 v178, v178, v206
	v_and_b32_e32 v206, 0xffff0000, v80
	v_add_f32_e32 v178, v178, v206
	v_and_b32_e32 v206, 0xffff0000, v88
	v_add_f32_e32 v178, v178, v206
	v_and_b32_e32 v206, 0xffff0000, v96
	v_add_f32_e32 v178, v178, v206
	v_lshlrev_b32_e32 v179, 16, v41
	v_lshlrev_b32_e32 v206, 16, v49
	v_add_f32_e32 v179, v179, v206
	v_lshlrev_b32_e32 v206, 16, v57
	v_add_f32_e32 v179, v179, v206
	v_lshlrev_b32_e32 v206, 16, v65
	v_add_f32_e32 v179, v179, v206
	v_lshlrev_b32_e32 v206, 16, v73
	v_add_f32_e32 v179, v179, v206
	v_lshlrev_b32_e32 v206, 16, v81
	v_add_f32_e32 v179, v179, v206
	v_lshlrev_b32_e32 v206, 16, v89
	v_add_f32_e32 v179, v179, v206
	v_lshlrev_b32_e32 v206, 16, v97
	v_add_f32_e32 v179, v179, v206
	v_and_b32_e32 v180, 0xffff0000, v41
	v_and_b32_e32 v206, 0xffff0000, v49
	v_add_f32_e32 v180, v180, v206
	v_and_b32_e32 v206, 0xffff0000, v57
	v_add_f32_e32 v180, v180, v206
	v_and_b32_e32 v206, 0xffff0000, v65
	v_add_f32_e32 v180, v180, v206
	v_and_b32_e32 v206, 0xffff0000, v73
	v_add_f32_e32 v180, v180, v206
	v_and_b32_e32 v206, 0xffff0000, v81
	v_add_f32_e32 v180, v180, v206
	v_and_b32_e32 v206, 0xffff0000, v89
	v_add_f32_e32 v180, v180, v206
; DI void phase_gla_norm(const Params& p, int g, int bid, int nb) {
;     ...
;       for (int m = 0; m < 2; ++m) {
;         float acc[16], lsum = 0.f;
; #pragma unroll
;         for (int e = 0; e < 16; ++e) acc[e] = 0.f;
; #pragma unroll
;         for (int j = 0; j < SPLIT_SP; ++j) {
;           const int sub = x * 64 + (ai0 + m) * SPLIT_SP + j;
;           lsum += pl[sub * 128 + row];
;           const bf16_t* src = po + (size_t)sub * 16384 + row * 128 + (lane & 7) * 16;
;           unpack8(*(const u32x4*)src, t);
; #pragma unroll
;           for (int e = 0; e < 8; ++e) acc[e] += t[e];
;           unpack8(*(const u32x4*)(src + 8), t);
; #pragma unroll
;           for (int e = 0; e < 8; ++e) acc[8 + e] += t[e];
;         }
	v_and_b32_e32 v206, 0xffff0000, v97
	v_add_f32_e32 v180, v180, v206
	v_lshlrev_b32_e32 v181, 16, v42
	v_lshlrev_b32_e32 v206, 16, v50
	v_add_f32_e32 v181, v181, v206
	v_lshlrev_b32_e32 v206, 16, v58
	v_add_f32_e32 v181, v181, v206
	v_lshlrev_b32_e32 v206, 16, v66
	v_add_f32_e32 v181, v181, v206
	v_lshlrev_b32_e32 v206, 16, v74
	v_add_f32_e32 v181, v181, v206
	v_lshlrev_b32_e32 v206, 16, v82
	v_add_f32_e32 v181, v181, v206
	v_lshlrev_b32_e32 v206, 16, v90
	v_add_f32_e32 v181, v181, v206
	v_lshlrev_b32_e32 v206, 16, v98
	v_add_f32_e32 v181, v181, v206
	v_and_b32_e32 v182, 0xffff0000, v42
	v_and_b32_e32 v206, 0xffff0000, v50
	v_add_f32_e32 v182, v182, v206
	v_and_b32_e32 v206, 0xffff0000, v58
	v_add_f32_e32 v182, v182, v206
	v_and_b32_e32 v206, 0xffff0000, v66
	v_add_f32_e32 v182, v182, v206
	v_and_b32_e32 v206, 0xffff0000, v74
	v_add_f32_e32 v182, v182, v206
	v_and_b32_e32 v206, 0xffff0000, v82
	v_add_f32_e32 v182, v182, v206
	v_and_b32_e32 v206, 0xffff0000, v90
	v_add_f32_e32 v182, v182, v206
	v_and_b32_e32 v206, 0xffff0000, v98
	v_add_f32_e32 v182, v182, v206
	v_lshlrev_b32_e32 v183, 16, v43
	v_lshlrev_b32_e32 v206, 16, v51
	v_add_f32_e32 v183, v183, v206
	v_lshlrev_b32_e32 v206, 16, v59
	v_add_f32_e32 v183, v183, v206
	v_lshlrev_b32_e32 v206, 16, v67
	v_add_f32_e32 v183, v183, v206
	v_lshlrev_b32_e32 v206, 16, v75
	v_add_f32_e32 v183, v183, v206
	v_lshlrev_b32_e32 v206, 16, v83
	v_add_f32_e32 v183, v183, v206
	v_lshlrev_b32_e32 v206, 16, v91
	v_add_f32_e32 v183, v183, v206
	v_lshlrev_b32_e32 v206, 16, v99
	v_add_f32_e32 v183, v183, v206
	v_and_b32_e32 v184, 0xffff0000, v43
	v_and_b32_e32 v206, 0xffff0000, v51
	v_add_f32_e32 v184, v184, v206
	v_and_b32_e32 v206, 0xffff0000, v59
	v_add_f32_e32 v184, v184, v206
	v_and_b32_e32 v206, 0xffff0000, v67
	v_add_f32_e32 v184, v184, v206
	v_and_b32_e32 v206, 0xffff0000, v75
	v_add_f32_e32 v184, v184, v206
	v_and_b32_e32 v206, 0xffff0000, v83
	v_add_f32_e32 v184, v184, v206
	v_and_b32_e32 v206, 0xffff0000, v91
	v_add_f32_e32 v184, v184, v206
	v_and_b32_e32 v206, 0xffff0000, v99
	v_add_f32_e32 v184, v184, v206
	v_lshlrev_b32_e32 v185, 16, v44
	v_lshlrev_b32_e32 v206, 16, v52
	v_add_f32_e32 v185, v185, v206
	v_lshlrev_b32_e32 v206, 16, v60
	v_add_f32_e32 v185, v185, v206
	v_lshlrev_b32_e32 v206, 16, v68
	v_add_f32_e32 v185, v185, v206
	v_lshlrev_b32_e32 v206, 16, v76
	v_add_f32_e32 v185, v185, v206
	v_lshlrev_b32_e32 v206, 16, v84
	v_add_f32_e32 v185, v185, v206
	v_lshlrev_b32_e32 v206, 16, v92
	v_add_f32_e32 v185, v185, v206
	v_lshlrev_b32_e32 v206, 16, v100
	v_add_f32_e32 v185, v185, v206
	v_and_b32_e32 v186, 0xffff0000, v44
	v_and_b32_e32 v206, 0xffff0000, v52
	v_add_f32_e32 v186, v186, v206
	v_and_b32_e32 v206, 0xffff0000, v60
	v_add_f32_e32 v186, v186, v206
	v_and_b32_e32 v206, 0xffff0000, v68
	v_add_f32_e32 v186, v186, v206
	v_and_b32_e32 v206, 0xffff0000, v76
	v_add_f32_e32 v186, v186, v206
	v_and_b32_e32 v206, 0xffff0000, v84
	v_add_f32_e32 v186, v186, v206
	v_and_b32_e32 v206, 0xffff0000, v92
	v_add_f32_e32 v186, v186, v206
	v_and_b32_e32 v206, 0xffff0000, v100
	v_add_f32_e32 v186, v186, v206
	v_lshlrev_b32_e32 v187, 16, v45
	v_lshlrev_b32_e32 v206, 16, v53
	v_add_f32_e32 v187, v187, v206
	v_lshlrev_b32_e32 v206, 16, v61
	v_add_f32_e32 v187, v187, v206
	v_lshlrev_b32_e32 v206, 16, v69
	v_add_f32_e32 v187, v187, v206
	v_lshlrev_b32_e32 v206, 16, v77
	v_add_f32_e32 v187, v187, v206
	v_lshlrev_b32_e32 v206, 16, v85
	v_add_f32_e32 v187, v187, v206
	v_lshlrev_b32_e32 v206, 16, v93
	v_add_f32_e32 v187, v187, v206
	v_lshlrev_b32_e32 v206, 16, v101
	v_add_f32_e32 v187, v187, v206
	v_and_b32_e32 v188, 0xffff0000, v45
	v_and_b32_e32 v206, 0xffff0000, v53
	v_add_f32_e32 v188, v188, v206
	v_and_b32_e32 v206, 0xffff0000, v61
	v_add_f32_e32 v188, v188, v206
	v_and_b32_e32 v206, 0xffff0000, v69
	v_add_f32_e32 v188, v188, v206
	v_and_b32_e32 v206, 0xffff0000, v77
	v_add_f32_e32 v188, v188, v206
	v_and_b32_e32 v206, 0xffff0000, v85
	v_add_f32_e32 v188, v188, v206
	v_and_b32_e32 v206, 0xffff0000, v93
	v_add_f32_e32 v188, v188, v206
	v_and_b32_e32 v206, 0xffff0000, v101
	v_add_f32_e32 v188, v188, v206
	v_lshlrev_b32_e32 v189, 16, v46
	v_lshlrev_b32_e32 v206, 16, v54
; DI void phase_gla_norm(const Params& p, int g, int bid, int nb) {
;     ...
;       for (int m = 0; m < 2; ++m) {
;         float acc[16], lsum = 0.f;
; #pragma unroll
;         for (int e = 0; e < 16; ++e) acc[e] = 0.f;
; #pragma unroll
;         for (int j = 0; j < SPLIT_SP; ++j) {
;           const int sub = x * 64 + (ai0 + m) * SPLIT_SP + j;
;           lsum += pl[sub * 128 + row];
;           const bf16_t* src = po + (size_t)sub * 16384 + row * 128 + (lane & 7) * 16;
;           unpack8(*(const u32x4*)src, t);
; #pragma unroll
;           for (int e = 0; e < 8; ++e) acc[e] += t[e];
;           unpack8(*(const u32x4*)(src + 8), t);
; #pragma unroll
;           for (int e = 0; e < 8; ++e) acc[8 + e] += t[e];
;         }
;         const float sc = (m == 0) ? (1.f / lsum) : (-lam / lsum);
; #pragma unroll
;         for (int e = 0; e < 16; ++e) { if (m == 0) w[e] = acc[e] * sc; else w[e] += acc[e] * sc; }
	v_add_f32_e32 v189, v189, v206
	v_lshlrev_b32_e32 v206, 16, v62
	v_add_f32_e32 v189, v189, v206
	v_lshlrev_b32_e32 v206, 16, v70
	v_add_f32_e32 v189, v189, v206
	v_lshlrev_b32_e32 v206, 16, v78
	v_add_f32_e32 v189, v189, v206
	v_lshlrev_b32_e32 v206, 16, v86
	v_add_f32_e32 v189, v189, v206
	v_lshlrev_b32_e32 v206, 16, v94
	v_add_f32_e32 v189, v189, v206
	v_lshlrev_b32_e32 v206, 16, v102
	v_add_f32_e32 v189, v189, v206
	v_and_b32_e32 v190, 0xffff0000, v46
	v_and_b32_e32 v206, 0xffff0000, v54
	v_add_f32_e32 v190, v190, v206
	v_and_b32_e32 v206, 0xffff0000, v62
	v_add_f32_e32 v190, v190, v206
	v_and_b32_e32 v206, 0xffff0000, v70
	v_add_f32_e32 v190, v190, v206
	v_and_b32_e32 v206, 0xffff0000, v78
	v_add_f32_e32 v190, v190, v206
	v_and_b32_e32 v206, 0xffff0000, v86
	v_add_f32_e32 v190, v190, v206
	v_and_b32_e32 v206, 0xffff0000, v94
	v_add_f32_e32 v190, v190, v206
	v_and_b32_e32 v206, 0xffff0000, v102
	v_add_f32_e32 v190, v190, v206
	v_lshlrev_b32_e32 v191, 16, v47
	v_lshlrev_b32_e32 v206, 16, v55
	v_add_f32_e32 v191, v191, v206
	v_lshlrev_b32_e32 v206, 16, v63
	v_add_f32_e32 v191, v191, v206
	v_lshlrev_b32_e32 v206, 16, v71
	v_add_f32_e32 v191, v191, v206
	v_lshlrev_b32_e32 v206, 16, v79
	v_add_f32_e32 v191, v191, v206
	v_lshlrev_b32_e32 v206, 16, v87
	v_add_f32_e32 v191, v191, v206
	v_lshlrev_b32_e32 v206, 16, v95
	v_add_f32_e32 v191, v191, v206
	v_lshlrev_b32_e32 v206, 16, v103
	v_add_f32_e32 v191, v191, v206
	v_and_b32_e32 v197, 0xffff0000, v47
	v_and_b32_e32 v206, 0xffff0000, v55
	v_add_f32_e32 v197, v197, v206
	v_and_b32_e32 v206, 0xffff0000, v63
	v_add_f32_e32 v197, v197, v206
	v_and_b32_e32 v206, 0xffff0000, v71
	v_add_f32_e32 v197, v197, v206
	v_and_b32_e32 v206, 0xffff0000, v79
	v_add_f32_e32 v197, v197, v206
	v_and_b32_e32 v206, 0xffff0000, v87
	v_add_f32_e32 v197, v197, v206
	v_and_b32_e32 v206, 0xffff0000, v95
	v_add_f32_e32 v197, v197, v206
	v_and_b32_e32 v206, 0xffff0000, v103
	v_add_f32_e32 v197, v197, v206
	v_add_f32_e32 v138, v138, v139
	v_add_f32_e32 v138, v138, v140
	v_add_f32_e32 v138, v138, v141
	v_add_f32_e32 v138, v138, v142
	v_add_f32_e32 v138, v138, v143
	v_add_f32_e32 v138, v138, v144
	v_add_f32_e32 v138, v138, v145
	v_add_f32_e32 v146, v146, v147
	v_add_f32_e32 v146, v146, v156
	v_add_f32_e32 v146, v146, v157
	v_add_f32_e32 v146, v146, v158
	v_add_f32_e32 v146, v146, v159
	v_add_f32_e32 v146, v146, v160
	v_add_f32_e32 v146, v146, v196
	v_div_scale_f32 v40, s[10:11], v138, v138, 1.0
	v_rcp_f32_e32 v41, v40
	s_nop 0
	v_fma_f32 v42, -v40, v41, 1.0
	v_fmac_f32_e32 v41, v42, v41
	v_div_scale_f32 v42, vcc, 1.0, v138, 1.0
	v_mul_f32_e32 v43, v42, v41
	v_fma_f32 v44, -v40, v43, v42
	v_fmac_f32_e32 v43, v44, v41
	v_fma_f32 v40, -v40, v43, v42
	v_div_fmas_f32 v40, v40, v41, v43
	v_div_fixup_f32 v207, v40, v138, 1.0
	v_div_scale_f32 v40, s[10:11], v146, v146, v149
	v_rcp_f32_e32 v41, v40
	s_nop 0
	v_fma_f32 v42, -v40, v41, 1.0
	v_fmac_f32_e32 v41, v42, v41
	v_div_scale_f32 v42, vcc, v149, v146, v149
	v_mul_f32_e32 v43, v42, v41
	v_fma_f32 v44, -v40, v43, v42
	v_fmac_f32_e32 v43, v44, v41
	v_fma_f32 v40, -v40, v43, v42
	v_div_fmas_f32 v40, v40, v41, v43
	v_div_fixup_f32 v208, v40, v146, v149
	v_mul_f32_e32 v44, v161, v207
	v_mul_f32_e32 v45, v162, v207
	v_mul_f32_e32 v46, v163, v207
	v_mul_f32_e32 v47, v164, v207
	v_mul_f32_e32 v48, v165, v207
	v_mul_f32_e32 v49, v166, v207
	v_mul_f32_e32 v50, v167, v207
	v_mul_f32_e32 v51, v168, v207
	v_mul_f32_e32 v52, v169, v207
	v_mul_f32_e32 v53, v170, v207
	v_mul_f32_e32 v40, v171, v207
	v_mul_f32_e32 v41, v172, v207
	v_mul_f32_e32 v54, v173, v207
	v_mul_f32_e32 v55, v174, v207
	v_mul_f32_e32 v42, v175, v207
	v_mul_f32_e32 v43, v176, v207
	v_fmac_f32_e32 v44, v177, v208
	v_fmac_f32_e32 v45, v178, v208
	v_fmac_f32_e32 v46, v179, v208
	v_fmac_f32_e32 v47, v180, v208
	v_fmac_f32_e32 v48, v181, v208
	v_fmac_f32_e32 v49, v182, v208
	v_fmac_f32_e32 v50, v183, v208
	v_fmac_f32_e32 v51, v184, v208
	v_fmac_f32_e32 v52, v185, v208
	v_fmac_f32_e32 v53, v186, v208
	v_fmac_f32_e32 v40, v187, v208
	v_fmac_f32_e32 v41, v188, v208
	v_fmac_f32_e32 v54, v189, v208
	v_fmac_f32_e32 v55, v190, v208
	v_fmac_f32_e32 v42, v191, v208
	v_fmac_f32_e32 v43, v197, v208
	s_branch .LBB0_233

; __device__ __forceinline__ int TID() { int t = threadIdx.x; asm volatile("" : "+v"(t)); return t; }
; DI void attn_item(const Params& p, int g, int seq, int hd, int qt, int m, char* smem, int split_j, int sub) {
;     ...
;   const int tid = TID(), lane = tid & 63, wave = __builtin_amdgcn_readfirstlane(tid >> 6), h_ = lane >> 5, l31_ = lane & 31;
;   __syncthreads();
;   for (int i = tid; i < 257; i += 256) tab[i] = p.rel_bias[t5_bucket(i - 128) * 8 + hd] * LOG2E;
;   const float cneg = p.rel_bias[15 * 8 + hd] * LOG2E, cpos = p.rel_bias[31 * 8 + hd] * LOG2E;
;   const bf16_t* qrow = proj + (size_t)(sb + q0 + wave * 32 + l31_) * NPROJ + hd * 128 + h_ * 8;
;   const int kr0 = tid >> 3, kc = (tid & 7) * 8;
;   const int vr0 = tid >> 2, vc = (tid & 3) * 8;
;   const bf16_t* vsrc = vaT + (size_t)(hd * 512 + (sb >> 5)) * 4096 + tid * 8;
;   const int npairs = (split_j < 0) ? (S >> 6) : (S >> 6) / SPLIT_SP;
;   const int tbase = (split_j < 0) ? 0 : split_j * npairs * 2;
;   const int qw0 = q0 + wave * 32;
;   bf16x8 qf[4];
; #pragma unroll
;   for (int s = 0; s < 4; ++s) qf[s] = *(const bf16x8*)(qrow + m * 64 + s * 16);
;   f32x16 O[4];
; #pragma unroll
;   for (int dt = 0; dt < 4; ++dt)
; #pragma unroll
;     for (int r = 0; r < 16; ++r) O[dt][r] = 0.f;
;   f32x2 ls2 = {0.f, 0.f};
;   int region = 0;
;   const bf16_t* ksrc = (const bf16_t*)(p.ws + OFF_KBLK) + (size_t)((hd * 2 + m) * 512 + (sb >> 5)) * 2048 + tid * 8;
;   u32x4 rkA, rvA0, rvA1, rkB, rvB0, rvB1;
;   auto load_tile = [&](int t, u32x4& k, u32x4& v0, u32x4& v1) __attribute__((always_inline)) {
;     k = *(const u32x4*)(ksrc + (size_t)(tbase + t) * 2048);
;     v0 = *(const u32x4*)(vsrc + (size_t)(tbase + t) * 4096); v1 = *(const u32x4*)(vsrc + (size_t)(tbase + t) * 4096 + 2048);
;   };
;     ...
;   load_tile(0, rkA, rvA0, rvA1);
;   load_tile(1, rkB, rvB0, rvB1);
;   __syncthreads();
;   store_tile(0, rkA, rvA0, rvA1);
;   store_tile(1, rkB, rvB0, rvB1);
;   __syncthreads();
;   for (int it = 0; it < npairs; ++it) {
.LBB0_264:
	s_or_b64 exec, exec, s[6:7]
	v_readlane_b32 s0, v231, 30
	s_sub_i32 s1, s12, s0
	s_lshr_b32 s0, s1, 3
	v_readlane_b32 s6, v231, 29
	s_add_i32 s0, s0, s6
	s_lshr_b32 s0, s0, 1
	v_readlane_b32 s6, v231, 32
	v_readlane_b32 s7, v231, 33
	s_lshr_b32 s6, s0, s6
	s_and_b32 s0, s0, s7
	v_readlane_b32 s7, v231, 37
	s_lshl_b32 s9, s6, s7
	v_readlane_b32 s6, v233, 14
	s_lshl_b32 s14, s0, 7
	v_readlane_b32 s7, v233, 15
	v_and_b32_e32 v168, 31, v0
	s_nop 3
	global_load_dword v1, v193, s[6:7] offset:480
	global_load_dword v10, v193, s[6:7] offset:992
	s_add_i32 s6, s14, s9
	s_ashr_i32 s0, s13, 1
	v_or_b32_e32 v2, s6, v168
	v_readlane_b32 s6, v233, 16
	s_andn2_b32 s0, s0, 31
	v_readlane_b32 s7, v233, 17
	v_add_u32_e32 v4, s0, v2
	s_bfe_u32 s8, s1, 0x10003
	v_mov_b64_e32 v[2:3], s[6:7]
	v_mad_i64_i32 v[2:3], s[6:7], v4, s2, v[2:3]
	s_lshl_b32 s7, s1, 1
	s_lshl_b32 s6, s9, 8
	v_readlane_b32 s11, v233, 13
	s_and_b32 s7, s7, 14
	v_readlane_b32 s10, v231, 38
	v_lshlrev_b32_e32 v4, 3, v0
	s_add_i32 s6, s6, s11
	s_lshl_b32 s10, s7, s10
	s_lshl_b32 s50, s8, 7
	v_ashrrev_i32_e32 v5, 31, v4
	s_add_u32 s6, s60, s6
	s_addc_u32 s7, s61, 0
	v_lshlrev_b64 v[6:7], 1, v[4:5]
	v_lshl_add_u64 v[176:177], s[6:7], 0, v[6:7]
	s_lshl_b32 s6, s8, 21
	s_lshl_b32 s7, s9, 7
	s_or_b32 s6, s6, s11
	v_bfe_u32 v188, v0, 5, 1
	s_add_i32 s6, s6, s7
	v_readlane_b32 s8, v233, 18
	v_lshlrev_b32_e32 v192, 4, v188
	v_readlane_b32 s9, v233, 19
	s_add_u32 s6, s8, s6
	v_lshl_add_u64 v[2:3], v[2:3], 0, v[192:193]
	s_addc_u32 s7, s9, 0
	v_lshl_add_u64 v[2:3], v[2:3], 0, s[50:51]
	v_lshl_add_u64 v[178:179], s[6:7], 0, v[6:7]
	s_lshl_b32 s50, s10, 12
	v_lshl_add_u64 v[6:7], v[178:179], 0, s[50:51]
	s_lshl_b32 s50, s10, 13
	v_lshl_add_u64 v[8:9], v[176:177], 0, s[50:51]
	global_load_dwordx4 v[96:99], v[6:7], off
	global_load_dwordx4 v[100:103], v[8:9], off
	v_add_co_u32_e32 v6, vcc, s81, v8
	s_or_b32 s6, s10, 1
	s_nop 0
	v_addc_co_u32_e32 v7, vcc, 0, v9, vcc
	s_lshl_b32 s50, s6, 12
	v_lshl_add_u64 v[8:9], v[178:179], 0, s[50:51]
	global_load_dwordx4 v[120:123], v[6:7], off
	global_load_dwordx4 v[124:127], v[8:9], off
	s_lshl_b32 s50, s6, 13
	v_lshl_add_u64 v[6:7], v[176:177], 0, s[50:51]
	v_add_co_u32_e32 v8, vcc, s81, v6
	v_and_b32_e32 v4, 24, v4
	s_nop 0
	v_addc_co_u32_e32 v9, vcc, 0, v7, vcc
	global_load_dwordx4 v[128:131], v[6:7], off
	global_load_dwordx4 v[132:135], v[8:9], off
	global_load_dwordx4 v[104:107], v[2:3], off
	global_load_dwordx4 v[108:111], v[2:3], off offset:32
	global_load_dwordx4 v[112:115], v[2:3], off offset:64
	global_load_dwordx4 v[116:119], v[2:3], off offset:96
	v_lshrrev_b32_e32 v2, 2, v0
	v_lshrrev_b32_e32 v3, 3, v0
	v_lshlrev_b32_e32 v0, 4, v0
	v_mul_lo_u32 v3, v3, s22
	v_and_b32_e32 v0, 0x70, v0
	v_mul_lo_u32 v2, v2, 40
	v_mul_u32_u24_e32 v5, 40, v168
	v_add3_u32 v189, 32, v3, v0
	v_lshlrev_b32_e32 v190, 1, v2
	v_lshlrev_b32_e32 v191, 1, v4
	v_add_u32_e32 v0, 32, v192
	s_add_i32 s14, s14, s0
	v_add3_u32 v2, 32, v190, v191
	v_mad_u32_u24 v196, v168, s22, v0
	v_lshl_add_u32 v197, v5, 1, v0
	v_or_b32_e32 v0, s14, v168
	v_mov_b32_e32 v14, v193
	v_mov_b32_e32 v15, v193
	s_waitcnt vmcnt(11) lgkmcnt(0)
	v_mul_f32_e32 v1, 0x3fb8aa3b, v1
	s_waitcnt vmcnt(10)
	v_mul_f32_e32 v169, 0x3fb8aa3b, v10
	v_exp_f32_e32 v170, v1
	v_exp_f32_e64 v180, -v169
	v_lshlrev_b32_e32 v1, 2, v188
	s_barrier
	v_sub_u32_e32 v198, v1, v0
	v_mov_b32_e32 v192, v193
	v_mov_b32_e32 v0, v193
	v_mov_b32_e32 v1, v193
	v_mov_b32_e32 v3, v193
	v_mov_b32_e32 v4, v193
	s_waitcnt vmcnt(9)
	ds_write_b128 v189, v[96:99]
	s_waitcnt vmcnt(8)
	ds_write_b128 v2, v[100:103] offset:18432
	s_waitcnt vmcnt(7)
	ds_write_b128 v2, v[120:123] offset:23552
	s_waitcnt vmcnt(6)
	ds_write_b128 v189, v[124:127] offset:4608
	s_waitcnt vmcnt(5)
	ds_write_b128 v2, v[128:131] offset:28672
	s_waitcnt vmcnt(4)
	ds_write_b128 v2, v[132:135] offset:33792
	v_mov_b32_e32 v2, v193
	v_mov_b32_e32 v5, v193
	v_mov_b32_e32 v6, v193
	v_mov_b32_e32 v7, v193
	v_mov_b32_e32 v8, v193
	v_mov_b32_e32 v9, v193
	v_mov_b32_e32 v10, v193
	v_mov_b32_e32 v11, v193
	v_mov_b32_e32 v12, v193
	v_mov_b32_e32 v13, v193
	v_mov_b64_e32 v[62:63], v[14:15]
	v_mov_b64_e32 v[46:47], v[14:15]
	v_mov_b64_e32 v[30:31], v[14:15]
	s_mov_b32 s11, 0
	v_mov_b32_e32 v172, v170
	v_mov_b32_e32 v173, v170
	v_mov_b32_e32 v182, v180
	v_mov_b32_e32 v183, v180
	v_mov_b32_e32 v174, v170
	v_mov_b32_e32 v175, v170
	v_mov_b32_e32 v184, v180
	v_mov_b32_e32 v185, v180
	s_lshl_b32 s13, s10, 5
	s_sub_i32 s14, 0, s14
	v_mov_b64_e32 v[60:61], v[12:13]
	v_mov_b64_e32 v[58:59], v[10:11]
	v_mov_b64_e32 v[56:57], v[8:9]
	v_mov_b64_e32 v[54:55], v[6:7]
	v_mov_b64_e32 v[52:53], v[4:5]
	v_mov_b64_e32 v[50:51], v[2:3]
	v_mov_b64_e32 v[48:49], v[0:1]
	v_mov_b64_e32 v[44:45], v[12:13]
	v_mov_b64_e32 v[42:43], v[10:11]
	v_mov_b64_e32 v[40:41], v[8:9]
	v_mov_b64_e32 v[38:39], v[6:7]
	v_mov_b64_e32 v[36:37], v[4:5]
	v_mov_b64_e32 v[34:35], v[2:3]
	v_mov_b64_e32 v[32:33], v[0:1]
	v_mov_b64_e32 v[28:29], v[12:13]
	v_mov_b64_e32 v[26:27], v[10:11]
	v_mov_b64_e32 v[24:25], v[8:9]
	v_mov_b64_e32 v[22:23], v[6:7]
	v_mov_b64_e32 v[20:21], v[4:5]
	v_mov_b64_e32 v[18:19], v[2:3]
	v_mov_b64_e32 v[16:17], v[0:1]
	s_mov_b32 s15, 0
	s_mov_b32 s16, 0
	v_mov_b64_e32 v[186:187], v[192:193]
	s_waitcnt vmcnt(0) lgkmcnt(0)
	s_add_i32 s15, s15, 1
	s_cmp_lt_u32 s15, s77
	s_cselect_b64 s[6:7], -1, 0
	s_cmp_ge_u32 s15, s77
	s_cbranch_scc1 .Lar_p
	s_add_i32 s17, s10, s11
	s_add_i32 s50, s17, 2
	s_lshl_b64 s[8:9], s[50:51], 12
	v_lshl_add_u64 v[236:237], v[178:179], 0, s[8:9]
	s_lshl_b64 s[8:9], s[50:51], 13
	v_lshl_add_u64 v[238:239], v[176:177], 0, s[8:9]
	s_add_i32 s50, s17, 3
	global_load_dwordx4 v[96:99], v[236:237], off
	global_load_dwordx4 v[100:103], v[238:239], off
	v_add_co_u32_e32 v236, vcc, 0x1000, v238
	s_lshl_b64 s[8:9], s[50:51], 12
	s_nop 0
	v_addc_co_u32_e32 v237, vcc, 0, v239, vcc
	v_lshl_add_u64 v[238:239], v[178:179], 0, s[8:9]
	s_lshl_b64 s[8:9], s[50:51], 13
	global_load_dwordx4 v[120:123], v[236:237], off
	global_load_dwordx4 v[124:127], v[238:239], off
	v_lshl_add_u64 v[236:237], v[176:177], 0, s[8:9]
	v_add_co_u32_e32 v238, vcc, 0x1000, v236
	s_nop 1
	v_addc_co_u32_e32 v239, vcc, 0, v237, vcc
	global_load_dwordx4 v[128:131], v[236:237], off
	global_load_dwordx4 v[132:135], v[238:239], off
